# P9 LN2 row loop: next row's loads prefetched one iteration ahead
# speedup vs baseline: 1.0007x; 1.0007x over previous
; __device__ __forceinline__ float bf_lo(unsigned w) { return __uint_as_float(w << 16); }
; __device__ __forceinline__ float bf_hi(unsigned w) { return __uint_as_float(w & 0xffff0000u); }
; #define GAS __attribute__((address_space(1)))
; __global__ void __launch_bounds__(NWAVES * 64) mega_fwd(Args args) {
;     ...
;         f32x4 g2v[4], b2v[4];
; #pragma unroll
;         for (int jj = 0; jj < 4; ++jj) { g2v[jj] = *(const f32x4*)(ln2_g + 256 * jj + 4 * lane); b2v[jj] = *(const f32x4*)(ln2_b + 256 * jj + 4 * lane); }
;     for (int row = gw; row < MROWS; row += NGW) {
;         GAS f32x4* zr = (GAS f32x4*)(out + (size_t)row * D) + lane;
;         const GAS unsigned long long* yr = (const GAS unsigned long long*)(Y2 + (size_t)row * D) + lane;
;         f32x4 v[4]; float s = 0.f;
; #pragma unroll
;         for (int j = 0; j < 4; ++j) { const f32x4 xv = __builtin_nontemporal_load(&zr[64 * j]); const unsigned long long yy = __builtin_nontemporal_load(&yr[64 * j]); const unsigned ylo = (unsigned)yy, yhi = (unsigned)(yy >> 32);
;             v[j] = xv * ALPHA + (f32x4){pg8::bf_lo(ylo), pg8::bf_hi(ylo), pg8::bf_lo(yhi), pg8::bf_hi(yhi)};
;             s += (v[j].x + v[j].y) + (v[j].z + v[j].w); }
.LBB0_744:
	s_or_b64 exec, exec, s[0:1]
	s_waitcnt lgkmcnt(0)
	s_barrier
	s_nop 0
	v_readfirstlane_b32 s0, v174
	s_ashr_i32 s0, s0, 6
	s_add_i32 s7, s0, s27
	s_cmp_lt_i32 s7, 0x10000
	s_cbranch_scc0 .LBB0_747
	v_and_b32_e32 v36, 63, v174
	v_readlane_b32 s8, v238, 0
	v_lshlrev_b32_e32 v34, 4, v36
	v_readlane_b32 s10, v238, 2
	v_readlane_b32 s11, v238, 3
	v_readlane_b32 s12, v238, 4
	v_readlane_b32 s13, v238, 5
	s_nop 2
	global_load_dwordx4 v[0:3], v34, s[10:11]
	s_nop 0
	global_load_dwordx4 v[4:7], v34, s[12:13]
	global_load_dwordx4 v[8:11], v34, s[10:11] offset:1024
	global_load_dwordx4 v[12:15], v34, s[12:13] offset:1024
	global_load_dwordx4 v[16:19], v34, s[10:11] offset:2048
	global_load_dwordx4 v[20:23], v34, s[12:13] offset:2048
	global_load_dwordx4 v[24:27], v34, s[10:11] offset:3072
	global_load_dwordx4 v[28:31], v34, s[12:13] offset:3072
	s_ashr_i32 s1, s0, 31
	s_ashr_i32 s2, s27, 31
	s_add_u32 s0, s0, s27
	s_addc_u32 s1, s1, s2
	v_readlane_b32 s14, v238, 6
	s_lshl_b64 s[2:3], s[0:1], 12
	v_readlane_b32 s15, v238, 7
	s_add_u32 s2, s14, s2
	v_lshlrev_b32_e32 v32, 2, v36
	v_mov_b32_e32 v35, 0
	s_addc_u32 s3, s15, s3
	v_xor_b32_e32 v52, 4, v32
	v_xor_b32_e32 v53, 8, v32
	v_xor_b32_e32 v54, 16, v32
	v_xor_b32_e32 v55, 32, v32
	v_xor_b32_e32 v56, 64, v32
	v_xor_b32_e32 v57, 0x80, v32
	v_lshl_add_u64 v[32:33], s[2:3], 0, v[34:35]
	s_mov_b64 s[2:3], 0xc00
	s_ashr_i32 s35, s34, 31
	v_lshl_add_u64 v[32:33], v[32:33], 0, s[2:3]
	s_lshl_b64 s[2:3], s[34:35], 12
	s_lshl_b64 s[0:1], s[0:1], 11
	s_add_u32 s0, s68, s0
	v_lshlrev_b32_e32 v34, 3, v36
	s_addc_u32 s1, s69, s1
	v_lshl_add_u64 v[34:35], s[0:1], 0, v[34:35]
	s_mov_b64 s[0:1], 0x2d000400
	v_lshl_add_u64 v[34:35], v[34:35], 0, s[0:1]
	s_lshl_b64 s[4:5], s[34:35], 11
	s_mov_b32 s6, 0x3f9837f0
	v_mov_b32_e32 v58, 0x3727c5ac
	s_mov_b32 s8, 0xf800000
	v_mov_b32_e32 v59, 0x260
	v_readlane_b32 s9, v238, 1
	global_load_dwordx2 v[78:79], v[34:35], off offset:-1024 nt
	global_load_dwordx2 v[80:81], v[34:35], off offset:-512 nt
	global_load_dwordx2 v[82:83], v[34:35], off nt
	global_load_dwordx2 v[84:85], v[34:35], off offset:512 nt
	global_load_dwordx4 v[86:89], v[32:33], off offset:-3072 nt
	global_load_dwordx4 v[90:93], v[32:33], off offset:-2048 nt
	global_load_dwordx4 v[94:97], v[32:33], off offset:-1024 nt
	global_load_dwordx4 v[98:101], v[32:33], off nt
	v_lshl_add_u64 v[34:35], v[34:35], 0, s[4:5]
	s_waitcnt vmcnt(0)
.LBB0_746:
	v_mov_b64_e32 v[40:41], v[78:79]
	v_mov_b64_e32 v[46:47], v[80:81]
	v_mov_b64_e32 v[64:65], v[82:83]
	v_mov_b64_e32 v[66:67], v[84:85]
	v_mov_b64_e32 v[36:37], v[86:87]
	v_mov_b64_e32 v[38:39], v[88:89]
	v_mov_b64_e32 v[42:43], v[90:91]
	v_mov_b64_e32 v[44:45], v[92:93]
	v_mov_b64_e32 v[48:49], v[94:95]
	v_mov_b64_e32 v[50:51], v[96:97]
	v_mov_b64_e32 v[60:61], v[98:99]
	v_mov_b64_e32 v[62:63], v[100:101]
	s_add_i32 s98, s7, s34
	s_cmp_gt_i32 s98, 0xffff
	s_cbranch_scc1 .Lp9_nopf
	v_lshl_add_u64 v[102:103], v[32:33], 0, s[2:3]
	global_load_dwordx2 v[78:79], v[34:35], off offset:-1024 nt
	global_load_dwordx2 v[80:81], v[34:35], off offset:-512 nt
	global_load_dwordx2 v[82:83], v[34:35], off nt
	global_load_dwordx2 v[84:85], v[34:35], off offset:512 nt
	global_load_dwordx4 v[86:89], v[102:103], off offset:-3072 nt
	global_load_dwordx4 v[90:93], v[102:103], off offset:-2048 nt
	global_load_dwordx4 v[94:97], v[102:103], off offset:-1024 nt
	global_load_dwordx4 v[98:101], v[102:103], off nt
.Lp9_nopf:
	v_lshl_add_u64 v[34:35], v[34:35], 0, s[4:5]
	v_lshlrev_b32_e32 v68, 16, v40
	v_and_b32_e32 v69, 0xffff0000, v40
	v_lshlrev_b32_e32 v40, 16, v41
	v_and_b32_e32 v41, 0xffff0000, v41
	v_lshlrev_b32_e32 v70, 16, v46
	v_and_b32_e32 v71, 0xffff0000, v46
	v_lshlrev_b32_e32 v72, 16, v47
	v_and_b32_e32 v73, 0xffff0000, v47
	v_lshlrev_b32_e32 v74, 16, v64
	v_and_b32_e32 v75, 0xffff0000, v64
	v_lshlrev_b32_e32 v64, 16, v65
	v_and_b32_e32 v65, 0xffff0000, v65
	v_lshlrev_b32_e32 v76, 16, v66
	v_and_b32_e32 v77, 0xffff0000, v66
	v_lshlrev_b32_e32 v66, 16, v67
	v_and_b32_e32 v67, 0xffff0000, v67
	v_pk_fma_f32 v[40:41], v[38:39], s[6:7], v[40:41] op_sel_hi:[1,0,1]
	v_pk_fma_f32 v[46:47], v[36:37], s[6:7], v[68:69] op_sel_hi:[1,0,1]
	v_pk_fma_f32 v[38:39], v[44:45], s[6:7], v[72:73] op_sel_hi:[1,0,1]
	v_pk_fma_f32 v[44:45], v[42:43], s[6:7], v[70:71] op_sel_hi:[1,0,1]
	v_pk_fma_f32 v[36:37], v[50:51], s[6:7], v[64:65] op_sel_hi:[1,0,1]
	v_pk_fma_f32 v[42:43], v[48:49], s[6:7], v[74:75] op_sel_hi:[1,0,1]
	v_pk_fma_f32 v[48:49], v[62:63], s[6:7], v[66:67] op_sel_hi:[1,0,1]
	v_pk_fma_f32 v[50:51], v[60:61], s[6:7], v[76:77] op_sel_hi:[1,0,1]
	v_pk_mov_b32 v[60:61], v[46:47], v[40:41] op_sel:[1,0]
	v_mov_b32_e32 v62, v46
	v_mov_b32_e32 v63, v41
	v_pk_mov_b32 v[64:65], v[44:45], v[38:39] op_sel:[1,0]
	v_mov_b32_e32 v66, v44
	v_mov_b32_e32 v67, v39
	v_pk_add_f32 v[60:61], v[60:61], v[62:63]
	v_pk_add_f32 v[62:63], v[64:65], v[66:67]
	v_add_f32_e32 v66, v60, v61
	v_pk_add_f32 v[60:61], v[62:63], v[62:63] op_sel:[0,1] op_sel_hi:[1,0]
	v_add_f32_e32 v68, v42, v43
	v_add_f32_e32 v70, v36, v37
	v_mov_b32_e32 v73, v50
	v_mov_b32_e32 v69, v48
	v_mov_b32_e32 v71, v49
	v_add_f32_e32 v72, 0, v66
	v_mov_b32_e32 v61, v51
	v_pk_add_f32 v[64:65], v[68:69], v[70:71]
	v_pk_add_f32 v[60:61], v[72:73], v[60:61]
	s_add_i32 s7, s7, s34
	v_pk_add_f32 v[60:61], v[60:61], v[64:65]
	s_cmp_gt_i32 s7, 0xffff
	v_add_f32_e32 v60, v60, v61
	s_waitcnt lgkmcnt(0)
; __global__ void __launch_bounds__(NWAVES * 64) mega_fwd(Args args) {
;     ...
;         const float mean = wave_sum(s, lane) * (1.f / D); float s2 = 0.f;
; #pragma unroll
;         for (int j = 0; j < 4; ++j) { v[j] = v[j] - mean; s2 += (v[j].x * v[j].x + v[j].y * v[j].y) + (v[j].z * v[j].z + v[j].w * v[j].w); }
;         const float rstd = 1.f / sqrtf(wave_sum(s2, lane) * (1.f / D) + LN_EPS);
; #pragma unroll
;         for (int j = 0; j < 4; ++j) { const f32x4 gg = g2v[j], bb = b2v[j];
;             __builtin_nontemporal_store(v[j] * rstd * gg + bb, &zr[64 * j]); }
	s_nop 1
	v_add_f32_dpp v60, v60, v60 quad_perm:[1,0,3,2] row_mask:0xf bank_mask:0xf
	s_waitcnt lgkmcnt(0)
	s_nop 1
	v_add_f32_dpp v60, v60, v60 quad_perm:[2,3,0,1] row_mask:0xf bank_mask:0xf
	s_waitcnt lgkmcnt(0)
	s_nop 1
	v_add_f32_dpp v60, v60, v60 row_half_mirror row_mask:0xf bank_mask:0xf
	s_waitcnt lgkmcnt(0)
	s_nop 1
	v_add_f32_dpp v60, v60, v60 row_mirror row_mask:0xf bank_mask:0xf
	s_waitcnt lgkmcnt(0)
	v_mov_b32_e32 v61, v60
	s_nop 1
	v_permlane16_swap_b32_e32 v60, v61
	v_add_f32_e32 v60, v60, v61
	s_waitcnt lgkmcnt(0)
	v_mov_b32_e32 v61, v60
	s_nop 1
	v_permlane32_swap_b32_e32 v60, v61
	v_add_f32_e32 v60, v60, v61
	v_fmamk_f32 v47, v60, 0xba800000, v47
	v_fmac_f32_e32 v46, 0xba800000, v60
	v_fmamk_f32 v41, v60, 0xba800000, v41
	v_fmac_f32_e32 v40, 0xba800000, v60
	v_fmamk_f32 v45, v60, 0xba800000, v45
	v_fmac_f32_e32 v44, 0xba800000, v60
	v_fmamk_f32 v39, v60, 0xba800000, v39
	v_fmac_f32_e32 v38, 0xba800000, v60
	v_fmamk_f32 v43, v60, 0xba800000, v43
	v_fmac_f32_e32 v42, 0xba800000, v60
	v_fmamk_f32 v37, v60, 0xba800000, v37
	v_fmac_f32_e32 v36, 0xba800000, v60
	v_fmamk_f32 v49, v60, 0xba800000, v49
	v_fmac_f32_e32 v48, 0xba800000, v60
	v_fmamk_f32 v51, v60, 0xba800000, v51
	v_fmac_f32_e32 v50, 0xba800000, v60
	v_pk_mul_f32 v[60:61], v[40:41], v[40:41]
	v_pk_mul_f32 v[62:63], v[46:47], v[46:47]
	v_pk_mul_f32 v[64:65], v[38:39], v[38:39]
	v_pk_mul_f32 v[66:67], v[44:45], v[44:45]
	v_pk_mov_b32 v[72:73], v[62:63], v[60:61] op_sel:[1,0]
	v_mov_b32_e32 v63, v61
	v_pk_mov_b32 v[60:61], v[66:67], v[64:65] op_sel:[1,0]
	v_mov_b32_e32 v67, v65
	v_mul_f32_e32 v71, v50, v50
	v_mul_f32_e32 v68, v43, v43
	v_mul_f32_e32 v70, v37, v37
	v_pk_add_f32 v[62:63], v[72:73], v[62:63]
	v_pk_add_f32 v[60:61], v[60:61], v[66:67]
	v_mul_f32_e32 v74, v51, v51
	v_mul_f32_e32 v75, v48, v48
	v_mul_f32_e32 v76, v49, v49
	v_pk_fma_f32 v[64:65], v[42:43], v[42:43], v[68:69] op_sel_hi:[1,1,0]
	v_pk_fma_f32 v[68:69], v[36:37], v[36:37], v[70:71] op_sel_hi:[1,1,0]
	v_pk_add_f32 v[62:63], v[62:63], v[62:63] op_sel:[0,1] op_sel_hi:[1,0]
	v_pk_add_f32 v[60:61], v[60:61], v[60:61] op_sel:[0,1] op_sel_hi:[1,0]
	v_mov_b32_e32 v65, v75
	v_mov_b32_e32 v69, v76
	v_mov_b32_e32 v63, v71
	v_mov_b32_e32 v61, v74
	v_pk_add_f32 v[64:65], v[64:65], v[68:69]
	v_pk_add_f32 v[60:61], v[62:63], v[60:61]
	s_nop 0
	v_pk_add_f32 v[60:61], v[60:61], v[64:65]
	s_nop 0
	v_add_f32_e32 v60, v60, v61
	s_waitcnt lgkmcnt(0)
	s_nop 1
	v_add_f32_dpp v60, v60, v60 quad_perm:[1,0,3,2] row_mask:0xf bank_mask:0xf
	s_waitcnt lgkmcnt(0)
	s_nop 1
	v_add_f32_dpp v60, v60, v60 quad_perm:[2,3,0,1] row_mask:0xf bank_mask:0xf
	s_waitcnt lgkmcnt(0)
	s_nop 1
	v_add_f32_dpp v60, v60, v60 row_half_mirror row_mask:0xf bank_mask:0xf
	s_waitcnt lgkmcnt(0)
	s_nop 1
	v_add_f32_dpp v60, v60, v60 row_mirror row_mask:0xf bank_mask:0xf
	s_waitcnt lgkmcnt(0)
	v_mov_b32_e32 v61, v60
	s_nop 1
	v_permlane16_swap_b32_e32 v60, v61
	v_add_f32_e32 v60, v60, v61
	s_waitcnt lgkmcnt(0)
	v_mov_b32_e32 v61, v60
	s_nop 1
	v_permlane32_swap_b32_e32 v60, v61
	v_add_f32_e32 v60, v60, v61
	v_fmamk_f32 v60, v60, 0x3a800000, v58
	v_mul_f32_e32 v61, 0x4f800000, v60
	v_cmp_gt_f32_e32 vcc, s8, v60
	s_nop 1
	v_cndmask_b32_e32 v60, v60, v61, vcc
	v_sqrt_f32_e32 v61, v60
	s_nop 0
	v_add_u32_e32 v62, -1, v61
	v_add_u32_e32 v63, 1, v61
	v_fma_f32 v64, -v62, v61, v60
	v_fma_f32 v65, -v63, v61, v60
	v_cmp_ge_f32_e64 s[0:1], 0, v64
	s_nop 1
	v_cndmask_b32_e64 v61, v61, v62, s[0:1]
	v_cmp_lt_f32_e64 s[0:1], 0, v65
	s_nop 1
	v_cndmask_b32_e64 v61, v61, v63, s[0:1]
	v_mul_f32_e32 v62, 0x37800000, v61
	v_cndmask_b32_e32 v61, v61, v62, vcc
	v_cmp_class_f32_e32 vcc, v60, v59
	s_nop 1
	v_cndmask_b32_e32 v60, v61, v60, vcc
	v_div_scale_f32 v61, s[0:1], v60, v60, 1.0
	v_rcp_f32_e32 v62, v61
	v_div_scale_f32 v63, vcc, 1.0, v60, 1.0
	v_fma_f32 v64, -v61, v62, 1.0
	v_fmac_f32_e32 v62, v64, v62
	v_mul_f32_e32 v64, v63, v62
	v_fma_f32 v65, -v61, v64, v63
	v_fmac_f32_e32 v64, v65, v62
	v_fma_f32 v61, -v61, v64, v63
	v_div_fmas_f32 v61, v61, v62, v64
	v_div_fixup_f32 v60, v61, v60, 1.0
	v_pk_mul_f32 v[46:47], v[60:61], v[46:47] op_sel_hi:[0,1]
	v_pk_mul_f32 v[40:41], v[60:61], v[40:41] op_sel_hi:[0,1]
	v_pk_mul_f32 v[44:45], v[60:61], v[44:45] op_sel_hi:[0,1]
	v_pk_mul_f32 v[62:63], v[60:61], v[38:39] op_sel_hi:[0,1]
	v_pk_mul_f32 v[64:65], v[60:61], v[42:43] op_sel_hi:[0,1]
	v_pk_mul_f32 v[66:67], v[60:61], v[36:37] op_sel_hi:[0,1]
	v_pk_mul_f32 v[68:69], v[60:61], v[50:51] op_sel_hi:[0,1]
	v_pk_mul_f32 v[48:49], v[60:61], v[48:49] op_sel_hi:[0,1]
	v_pk_fma_f32 v[38:39], v[40:41], v[2:3], v[6:7]
	v_pk_fma_f32 v[36:37], v[46:47], v[0:1], v[4:5]
	v_pk_fma_f32 v[42:43], v[62:63], v[10:11], v[14:15]
	v_pk_fma_f32 v[40:41], v[44:45], v[8:9], v[12:13]
	v_pk_fma_f32 v[46:47], v[66:67], v[18:19], v[22:23]
	v_pk_fma_f32 v[44:45], v[64:65], v[16:17], v[20:21]
	v_pk_fma_f32 v[50:51], v[48:49], v[26:27], v[30:31]
	v_pk_fma_f32 v[48:49], v[68:69], v[24:25], v[28:29]
	global_store_dwordx4 v[32:33], v[36:39], off offset:-3072 nt
	global_store_dwordx4 v[32:33], v[40:43], off offset:-2048 nt
	global_store_dwordx4 v[32:33], v[44:47], off offset:-1024 nt
	global_store_dwordx4 v[32:33], v[48:51], off nt
	v_lshl_add_u64 v[32:33], v[32:33], 0, s[2:3]
	s_waitcnt vmcnt(4)
	s_cbranch_scc0 .LBB0_746
